# P8/P9 unit headers fully closed-form with a scalar has-next test (about 14 SALU instead of 40 + two VALU compares)
# baseline (speedup 1.0000x reference)
;     __host__ __device__ bool next(int i, Unit& u) const { const int L = i * G + c; if (L >= n) return false; u.pm = L; u.pn = L >> 2; return true; }
;     __host__ __device__ bool next(int i, Unit& u) const {
;         const long L = (long)i * G + c; if (L >= nwg) return false;
;         int wgid = (int)L; { const int q = nwg / NXCD, r = nwg % NXCD, xcd = wgid % NXCD, off = wgid / NXCD; wgid = (xcd < r ? xcd * (q + 1) : r * (q + 1) + (xcd - r) * q) + off; }
;         const int nig = WGM * nN, gid = wgid / nig, fm = gid * WGM, gsz = (nM - fm) < WGM ? (nM - fm) : WGM;
;         u.pm = fm + ((wgid % nig) % gsz); u.pn = (wgid % nig) / gsz; return true;
;     }
; template <class Epi, class Sched, bool ALIGN_EPI>
; __device__ __forceinline__ void gemm_phase(PG8_LAS unsigned char* lds, const Gemm g, const Sched& S, const Epi& E) {
;     ...
;         const bool has_next = S.next(ui + 1, nxt);
;         const size_t tail_ = has_next ? 0 : tailoff; const char* nA = (has_next ? (const char*)g.A + (size_t)nxt.pm * tstepA : cA) + (has_next ? 0 : tailoffA); const char* nB = (has_next ? (const char*)g.Bt + (size_t)nxt.pn * tstepB : cB) + tail_;
.LBB0_898:
	s_add_i32 s42, s42, 1
	s_cmp_lt_u32 s42, 11
	s_cselect_b64 s[0:1], -1, 0
	s_cbranch_scc0 .Lh8_last
	s_add_i32 s18, s48, 4
	s_mov_b32 s20, s26
	s_mov_b64 s[22:23], s[28:29]
	s_add_u32 s24, s30, 0x400000
	s_addc_u32 s25, s31, 0
	s_branch .Lh8_join
.Lh8_last:
	s_add_u32 s22, s28, 0xf00
	s_addc_u32 s23, s29, 0
	s_add_u32 s24, s30, 0xf00
	s_addc_u32 s25, s31, 0
.Lh8_join:
	s_add_u32 s28, s28, 0x80080
	s_addc_u32 s29, s29, 0
	s_and_b32 s2, s3, 0xfff
	s_mov_b32 s49, 0
	s_cmp_lt_u32 s3, 0x1000
	s_cbranch_scc0 .Lp8k_B_init
	s_setprio 0
	s_mov_b64 s[50:51], s[24:25]
	s_cmp_eq_u32 s42, 1
	s_cbranch_scc1 .Lp8k_A_first
	s_add_u32 s28, s30, 0x100
	s_addc_u32 s29, s31, 0
	ds_read_b128 v[156:159], v153 offset:0
	ds_read_b128 v[160:163], v153 offset:1024
	s_branch .Lp8k_A_entry

;     __host__ __device__ bool next(int i, Unit& u) const { const int L = i * G + c; if (L >= n) return false; u.pm = L; u.pn = L >> 2; return true; }
;     __host__ __device__ bool next(int i, Unit& u) const {
;         const long L = (long)i * G + c; if (L >= nwg) return false;
;         int wgid = (int)L; { const int q = nwg / NXCD, r = nwg % NXCD, xcd = wgid % NXCD, off = wgid / NXCD; wgid = (xcd < r ? xcd * (q + 1) : r * (q + 1) + (xcd - r) * q) + off; }
;         const int nig = WGM * nN, gid = wgid / nig, fm = gid * WGM, gsz = (nM - fm) < WGM ? (nM - fm) : WGM;
;         u.pm = fm + ((wgid % nig) % gsz); u.pn = (wgid % nig) / gsz; return true;
;     }
; template <class Epi, class Sched, bool ALIGN_EPI>
; __device__ __forceinline__ void gemm_phase(PG8_LAS unsigned char* lds, const Gemm g, const Sched& S, const Epi& E) {
;     ...
;         const bool has_next = S.next(ui + 1, nxt);
;         const size_t tail_ = has_next ? 0 : tailoff; const char* nA = (has_next ? (const char*)g.A + (size_t)nxt.pm * tstepA : cA) + (has_next ? 0 : tailoffA); const char* nB = (has_next ? (const char*)g.Bt + (size_t)nxt.pn * tstepB : cB) + tail_;
.LBB0_937:
	s_add_i32 s42, s42, 1
	s_cmp_lt_u32 s42, 2
	s_cbranch_scc0 .Lh9_last
	s_mov_b64 s[0:1], 0
	s_add_i32 s53, s56, 4
	s_mov_b32 s54, s55
	s_mov_b64 s[6:7], s[26:27]
	s_add_u32 s24, s28, 0xb00000
	s_addc_u32 s25, s29, 0
	s_branch .Lh9_join
.Lh9_last:
	s_mov_b64 s[0:1], -1
	s_add_u32 s6, s26, 0x2b00
	s_addc_u32 s7, s27, 0
	s_add_u32 s24, s28, 0x2b00
	s_addc_u32 s25, s29, 0
.Lh9_join:
	s_and_b32 s60, s37, 0xfff
	s_mov_b32 s57, 0
	s_cmp_lt_u32 s37, 0x1000
	s_cbranch_scc0 .Lp9k_B_init
	s_setprio 0
	s_mov_b64 s[58:59], s[24:25]
	s_cmp_eq_u32 s42, 1
	s_cbranch_scc1 .Lp9k_A_first
	s_add_u32 s28, s28, 0x100
	s_addc_u32 s29, s29, 0
	ds_read_b128 v[158:161], v155 offset:0
	ds_read_b128 v[162:165], v155 offset:1024
	ds_read_b128 v[142:145], v157 offset:23552
	s_branch .Lp9k_A_entry
